# speedup vs baseline: 1.0414x; 1.0004x over previous
; DI float bflo(unsigned w) { return __uint_as_float(w << 16); }
; DI float bfhi(unsigned w) { return __uint_as_float(w & 0xffff0000u); }
; DI unsigned cvtpk(float lo, float hi) { unsigned r; asm volatile("v_cvt_pk_bf16_f32 %0, %1, %2" : "=v"(r) : "v"(lo), "v"(hi)); return r; }
; DI float sigmoidf_(float x) { return __builtin_amdgcn_rcpf(1.f + __expf(-x)); }
;     __device__ __forceinline__ void operator()(const f32x4 (&acc)[2][2][4][2], const Unit& u, int wr, int wc, int fr, int fq) const {
;     ...
;                 const int row = u.pm * BM + ai * HALF + wr * 64 + m * 16 + fr;
;                 const int colb = pn * BM + wc * 32 + 8 * fq;
;                 const unsigned goff = (unsigned)(row * LDP + C_GT + br * 1024 + colb), ooff = (unsigned)(row * 1024 + colb);
;                 const bf16_t* gp = proj + goff;
;                 bf16_t* op = out + ooff;
;                 __builtin_amdgcn_sched_barrier(0);
; #pragma unroll
;                 for (int bj = 0; bj < 2; ++bj) {
;                     const u32x4 g = *(const u32x4*)(gp + bj * HALF);
;                     f32x4 v0 = acc[ai][bj][m][0], v1 = acc[ai][bj][m][1];
;                     v0[0] *= sigmoidf_(bflo(g[0])); v0[1] *= sigmoidf_(bfhi(g[0])); v0[2] *= sigmoidf_(bflo(g[1])); v0[3] *= sigmoidf_(bfhi(g[1]));
;                     v1[0] *= sigmoidf_(bflo(g[2])); v1[1] *= sigmoidf_(bfhi(g[2])); v1[2] *= sigmoidf_(bflo(g[3])); v1[3] *= sigmoidf_(bfhi(g[3]));
;                     if (br > 0) {
;                         const u32x4 o = *(const u32x4*)(op + bj * HALF);
;                         v0[0] += bflo(o[0]); v0[1] += bfhi(o[0]); v0[2] += bflo(o[1]); v0[3] += bfhi(o[1]);
;                         v1[0] += bflo(o[2]); v1[1] += bfhi(o[2]); v1[2] += bflo(o[3]); v1[3] += bfhi(o[3]);
;                     }
;                     u32x4 w = {cvtpk(v0[0], v0[1]), cvtpk(v0[2], v0[3]), cvtpk(v1[0], v1[1]), cvtpk(v1[2], v1[3])};
;                     *(u32x4*)(op + bj * HALF) = w;
.LBB0_143:
	s_lshl_b32 s4, s24, 8
	s_ashr_i32 s6, s24, 2
	s_and_b32 s4, s4, 0x300
	v_or_b32_e32 v166, s4, v164
	s_lshl_b32 s4, s6, 10
	s_addk_i32 s4, 0x2000
	v_or_b32_e32 v167, s4, v166
	v_readlane_b32 s80, v255, 8
	s_cmp_gt_i32 s6, 0
	v_add_u32_e32 v0, v167, v147
	v_or_b32_e32 v142, v166, v148
	v_readlane_b32 s92, v255, 20
	v_readlane_b32 s93, v255, 21
	v_readlane_b32 s94, v255, 22
	v_readlane_b32 s95, v255, 23
	v_mov_b32_e32 v143, v1
	s_cselect_b64 s[4:5], -1, 0
	v_lshl_add_u64 v[144:145], v[0:1], 1, s[94:95]
	v_lshl_add_u64 v[142:143], v[142:143], 1, s[92:93]
	s_cmp_lt_i32 s6, 1
	v_readlane_b32 s81, v255, 9
	v_readlane_b32 s82, v255, 10
	v_readlane_b32 s83, v255, 11
	v_readlane_b32 s84, v255, 12
	v_readlane_b32 s85, v255, 13
	v_readlane_b32 s86, v255, 14
	v_readlane_b32 s87, v255, 15
	v_readlane_b32 s88, v255, 16
	v_readlane_b32 s89, v255, 17
	v_readlane_b32 s90, v255, 18
	v_readlane_b32 s91, v255, 19
	v_add_u32_e32 v178, v167, v147
	v_mov_b32_e32 v179, v1
	v_lshl_add_u64 v[178:179], v[178:179], 1, s[94:95]
	v_or_b32_e32 v180, v166, v148
	v_mov_b32_e32 v181, v1
	v_lshl_add_u64 v[180:181], v[180:181], 1, s[92:93]
	global_load_dwordx4 v[218:221], v[178:179], off
	global_load_dwordx4 v[222:225], v[178:179], off offset:256
	global_load_dwordx4 v[226:229], v[180:181], off
	global_load_dwordx4 v[230:233], v[180:181], off offset:256
	v_add_u32_e32 v178, v167, v149
	v_mov_b32_e32 v179, v1
	v_lshl_add_u64 v[178:179], v[178:179], 1, s[94:95]
	v_or_b32_e32 v180, v166, v150
	v_mov_b32_e32 v181, v1
	v_lshl_add_u64 v[180:181], v[180:181], 1, s[92:93]
	global_load_dwordx4 v[234:237], v[178:179], off
	global_load_dwordx4 v[238:241], v[178:179], off offset:256
	global_load_dwordx4 v[242:245], v[180:181], off
	global_load_dwordx4 v[174:177], v[180:181], off offset:256
	s_waitcnt vmcnt(7)
	v_mov_b32_e32 v168, v218
	v_mov_b32_e32 v169, v219
	v_mov_b32_e32 v170, v220
	v_mov_b32_e32 v171, v221
	v_lshlrev_b32_e32 v0, 16, v168
	v_mul_f32_e32 v0, 0xbfb8aa3b, v0
	v_exp_f32_e32 v0, v0
	s_nop 0
	v_add_f32_e32 v0, 1.0, v0
	v_rcp_f32_e32 v172, v0
	v_and_b32_e32 v0, 0xffff0000, v168
	v_mul_f32_e32 v0, 0xbfb8aa3b, v0
	v_exp_f32_e32 v0, v0
	s_nop 0
	v_add_f32_e32 v0, 1.0, v0
	v_rcp_f32_e32 v173, v0
	v_lshlrev_b32_e32 v0, 16, v169
	v_mul_f32_e32 v0, 0xbfb8aa3b, v0
	v_exp_f32_e32 v0, v0
	v_pk_mul_f32 v[126:127], v[126:127], v[172:173]
	v_add_f32_e32 v0, 1.0, v0
	v_rcp_f32_e32 v168, v0
	v_and_b32_e32 v0, 0xffff0000, v169
	v_mul_f32_e32 v0, 0xbfb8aa3b, v0
	v_exp_f32_e32 v0, v0
	s_nop 0
	v_add_f32_e32 v0, 1.0, v0
	v_rcp_f32_e32 v169, v0
	v_lshlrev_b32_e32 v0, 16, v170
	v_mul_f32_e32 v0, 0xbfb8aa3b, v0
	v_exp_f32_e32 v0, v0
	v_pk_mul_f32 v[128:129], v[128:129], v[168:169]
	v_add_f32_e32 v0, 1.0, v0
	v_rcp_f32_e32 v168, v0
	v_and_b32_e32 v0, 0xffff0000, v170
	v_mul_f32_e32 v0, 0xbfb8aa3b, v0
	v_exp_f32_e32 v0, v0
	s_nop 0
	v_add_f32_e32 v0, 1.0, v0
	v_rcp_f32_e32 v169, v0
	v_lshlrev_b32_e32 v0, 16, v171
	v_mul_f32_e32 v0, 0xbfb8aa3b, v0
	v_exp_f32_e32 v0, v0
	v_pk_mul_f32 v[122:123], v[122:123], v[168:169]
	v_add_f32_e32 v0, 1.0, v0
	v_rcp_f32_e32 v168, v0
	v_and_b32_e32 v0, 0xffff0000, v171
	v_mul_f32_e32 v0, 0xbfb8aa3b, v0
	v_exp_f32_e32 v0, v0
	s_nop 0
	v_add_f32_e32 v0, 1.0, v0
	v_rcp_f32_e32 v169, v0
	s_nop 0
	v_pk_mul_f32 v[124:125], v[124:125], v[168:169]
	s_cbranch_scc1 .LBB0_145
	s_waitcnt vmcnt(5)
	v_mov_b32_e32 v168, v226
	v_mov_b32_e32 v169, v227
	v_mov_b32_e32 v170, v228
	v_mov_b32_e32 v171, v229
	v_lshlrev_b32_e32 v172, 16, v168
	v_and_b32_e32 v173, 0xffff0000, v168
	v_lshlrev_b32_e32 v168, 16, v169
	v_and_b32_e32 v169, 0xffff0000, v169
	v_pk_add_f32 v[128:129], v[128:129], v[168:169]
	v_lshlrev_b32_e32 v168, 16, v170
	v_and_b32_e32 v169, 0xffff0000, v170
	v_pk_add_f32 v[122:123], v[122:123], v[168:169]
	v_lshlrev_b32_e32 v168, 16, v171
	v_and_b32_e32 v169, 0xffff0000, v171
	v_pk_add_f32 v[126:127], v[126:127], v[172:173]
	v_pk_add_f32 v[124:125], v[124:125], v[168:169]
.LBB0_145:
	v_cvt_pk_bf16_f32 v126, v126, v127
	v_cvt_pk_bf16_f32 v127, v128, v129
	v_cvt_pk_bf16_f32 v128, v122, v123
	s_nop 0
	v_cvt_pk_bf16_f32 v129, v124, v125
	global_store_dwordx4 v[142:143], v[126:129], off
	v_cndmask_b32_e64 v0, 0, 1, s[4:5]
	v_cmp_ne_u32_e64 s[36:37], 1, v0
	s_andn2_b64 vcc, exec, s[4:5]
	v_readlane_b32 s96, v255, 5
	s_brev_b32 s69, 18
	v_mov_b32_e32 v206, v208
	s_waitcnt vmcnt(6)
	v_mov_b32_e32 v122, v222
	v_mov_b32_e32 v123, v223
	v_mov_b32_e32 v124, v224
	v_mov_b32_e32 v125, v225
	v_lshlrev_b32_e32 v0, 16, v122
	v_and_b32_e32 v122, 0xffff0000, v122
	v_lshlrev_b32_e32 v126, 16, v123
	v_and_b32_e32 v123, 0xffff0000, v123
	v_lshlrev_b32_e32 v127, 16, v124
	v_and_b32_e32 v124, 0xffff0000, v124
	v_lshlrev_b32_e32 v128, 16, v125
	v_and_b32_e32 v125, 0xffff0000, v125
	v_mul_f32_e32 v0, 0xbfb8aa3b, v0
	v_mul_f32_e32 v122, 0xbfb8aa3b, v122
	v_mul_f32_e32 v126, 0xbfb8aa3b, v126
	v_mul_f32_e32 v123, 0xbfb8aa3b, v123
	v_mul_f32_e32 v127, 0xbfb8aa3b, v127
	v_mul_f32_e32 v124, 0xbfb8aa3b, v124
	v_mul_f32_e32 v128, 0xbfb8aa3b, v128
	v_mul_f32_e32 v125, 0xbfb8aa3b, v125
	v_exp_f32_e32 v0, v0
	v_exp_f32_e32 v122, v122
	v_exp_f32_e32 v126, v126
	v_exp_f32_e32 v123, v123
	v_exp_f32_e32 v127, v127
	v_exp_f32_e32 v124, v124
	v_exp_f32_e32 v128, v128
	v_exp_f32_e32 v125, v125
	v_add_f32_e32 v0, 1.0, v0
	v_add_f32_e32 v129, 1.0, v122
	v_add_f32_e32 v126, 1.0, v126
	v_add_f32_e32 v144, 1.0, v123
	v_add_f32_e32 v127, 1.0, v127
	v_add_f32_e32 v145, 1.0, v124
	v_add_f32_e32 v128, 1.0, v128
	v_add_f32_e32 v168, 1.0, v125
	v_rcp_f32_e32 v122, v0
	v_rcp_f32_e32 v123, v129
	v_rcp_f32_e32 v124, v126
	v_rcp_f32_e32 v125, v144
	v_rcp_f32_e32 v126, v127
	v_rcp_f32_e32 v127, v145
	v_rcp_f32_e32 v128, v128
	v_rcp_f32_e32 v129, v168
	v_pk_mul_f32 v[118:119], v[118:119], v[122:123]
	v_pk_mul_f32 v[120:121], v[120:121], v[124:125]
	v_pk_mul_f32 v[122:123], v[114:115], v[126:127]
	v_pk_mul_f32 v[114:115], v[116:117], v[128:129]
	s_cbranch_vccnz .LBB0_147
	s_waitcnt vmcnt(4)
	v_mov_b32_e32 v124, v230
	v_mov_b32_e32 v125, v231
	v_mov_b32_e32 v126, v232
	v_mov_b32_e32 v127, v233
	v_lshlrev_b32_e32 v116, 16, v124
	v_and_b32_e32 v117, 0xffff0000, v124
	v_pk_add_f32 v[118:119], v[118:119], v[116:117]
	v_lshlrev_b32_e32 v116, 16, v125
	v_and_b32_e32 v117, 0xffff0000, v125
	v_pk_add_f32 v[120:121], v[120:121], v[116:117]
	v_lshlrev_b32_e32 v116, 16, v126
	v_and_b32_e32 v117, 0xffff0000, v126
	v_pk_add_f32 v[122:123], v[122:123], v[116:117]
	v_lshlrev_b32_e32 v116, 16, v127
	v_and_b32_e32 v117, 0xffff0000, v127
	v_pk_add_f32 v[114:115], v[114:115], v[116:117]
; DI float bflo(unsigned w) { return __uint_as_float(w << 16); }
; DI float bfhi(unsigned w) { return __uint_as_float(w & 0xffff0000u); }
; DI unsigned cvtpk(float lo, float hi) { unsigned r; asm volatile("v_cvt_pk_bf16_f32 %0, %1, %2" : "=v"(r) : "v"(lo), "v"(hi)); return r; }
; DI float sigmoidf_(float x) { return __builtin_amdgcn_rcpf(1.f + __expf(-x)); }
;     __device__ __forceinline__ void operator()(const f32x4 (&acc)[2][2][4][2], const Unit& u, int wr, int wc, int fr, int fq) const {
;     ...
;                 const int row = u.pm * BM + ai * HALF + wr * 64 + m * 16 + fr;
;                 const int colb = pn * BM + wc * 32 + 8 * fq;
;                 const unsigned goff = (unsigned)(row * LDP + C_GT + br * 1024 + colb), ooff = (unsigned)(row * 1024 + colb);
;                 const bf16_t* gp = proj + goff;
;                 bf16_t* op = out + ooff;
;                 __builtin_amdgcn_sched_barrier(0);
; #pragma unroll
;                 for (int bj = 0; bj < 2; ++bj) {
;                     const u32x4 g = *(const u32x4*)(gp + bj * HALF);
;                     f32x4 v0 = acc[ai][bj][m][0], v1 = acc[ai][bj][m][1];
;                     v0[0] *= sigmoidf_(bflo(g[0])); v0[1] *= sigmoidf_(bfhi(g[0])); v0[2] *= sigmoidf_(bflo(g[1])); v0[3] *= sigmoidf_(bfhi(g[1]));
;                     v1[0] *= sigmoidf_(bflo(g[2])); v1[1] *= sigmoidf_(bfhi(g[2])); v1[2] *= sigmoidf_(bflo(g[3])); v1[3] *= sigmoidf_(bfhi(g[3]));
;                     if (br > 0) {
;                         const u32x4 o = *(const u32x4*)(op + bj * HALF);
;                         v0[0] += bflo(o[0]); v0[1] += bfhi(o[0]); v0[2] += bflo(o[1]); v0[3] += bfhi(o[1]);
;                         v1[0] += bflo(o[2]); v1[1] += bfhi(o[2]); v1[2] += bflo(o[3]); v1[3] += bfhi(o[3]);
;                     }
;                     u32x4 w = {cvtpk(v0[0], v0[1]), cvtpk(v0[2], v0[3]), cvtpk(v1[0], v1[1]), cvtpk(v1[2], v1[3])};
;                     *(u32x4*)(op + bj * HALF) = w;
.LBB0_147:
	v_readlane_b32 s80, v255, 8
	v_cvt_pk_bf16_f32 v116, v118, v119
	v_cvt_pk_bf16_f32 v117, v120, v121
	v_cvt_pk_bf16_f32 v118, v122, v123
	v_cvt_pk_bf16_f32 v119, v114, v115
	v_add_u32_e32 v0, v167, v149
	v_or_b32_e32 v114, v166, v150
	v_readlane_b32 s92, v255, 20
	v_readlane_b32 s93, v255, 21
	v_readlane_b32 s94, v255, 22
	v_readlane_b32 s95, v255, 23
	v_mov_b32_e32 v115, v1
	global_store_dwordx4 v[142:143], v[116:119], off offset:256
	v_lshl_add_u64 v[114:115], v[114:115], 1, s[92:93]
	v_readlane_b32 s81, v255, 9
	v_lshl_add_u64 v[116:117], v[0:1], 1, s[94:95]
	v_readlane_b32 s82, v255, 10
	v_readlane_b32 s83, v255, 11
	v_readlane_b32 s84, v255, 12
	v_readlane_b32 s85, v255, 13
	v_readlane_b32 s86, v255, 14
	v_readlane_b32 s87, v255, 15
	v_readlane_b32 s88, v255, 16
	v_readlane_b32 s89, v255, 17
	v_readlane_b32 s90, v255, 18
	v_readlane_b32 s91, v255, 19
	v_add_u32_e32 v178, v167, v151
	v_mov_b32_e32 v179, v1
	v_lshl_add_u64 v[178:179], v[178:179], 1, s[94:95]
	v_or_b32_e32 v180, v166, v152
	v_mov_b32_e32 v181, v1
	v_lshl_add_u64 v[180:181], v[180:181], 1, s[92:93]
	global_load_dwordx4 v[218:221], v[178:179], off
	global_load_dwordx4 v[222:225], v[178:179], off offset:256
	global_load_dwordx4 v[226:229], v[180:181], off
	global_load_dwordx4 v[230:233], v[180:181], off offset:256
	s_and_b64 vcc, exec, s[36:37]
	s_waitcnt vmcnt(7)
	v_mov_b32_e32 v118, v234
	v_mov_b32_e32 v119, v235
	v_mov_b32_e32 v120, v236
	v_mov_b32_e32 v121, v237
	v_lshlrev_b32_e32 v0, 16, v118
	v_mul_f32_e32 v0, 0xbfb8aa3b, v0
	v_exp_f32_e32 v0, v0
	s_nop 0
	v_add_f32_e32 v0, 1.0, v0
	v_rcp_f32_e32 v122, v0
	v_and_b32_e32 v0, 0xffff0000, v118
	v_mul_f32_e32 v0, 0xbfb8aa3b, v0
	v_exp_f32_e32 v0, v0
	s_nop 0
	v_add_f32_e32 v0, 1.0, v0
	v_rcp_f32_e32 v123, v0
	v_lshlrev_b32_e32 v0, 16, v119
	v_mul_f32_e32 v0, 0xbfb8aa3b, v0
	v_exp_f32_e32 v0, v0
	v_pk_mul_f32 v[110:111], v[110:111], v[122:123]
	v_add_f32_e32 v0, 1.0, v0
	v_rcp_f32_e32 v118, v0
	v_and_b32_e32 v0, 0xffff0000, v119
	v_mul_f32_e32 v0, 0xbfb8aa3b, v0
	v_exp_f32_e32 v0, v0
	s_nop 0
	v_add_f32_e32 v0, 1.0, v0
	v_rcp_f32_e32 v119, v0
	v_lshlrev_b32_e32 v0, 16, v120
	v_mul_f32_e32 v0, 0xbfb8aa3b, v0
	v_exp_f32_e32 v0, v0
	v_pk_mul_f32 v[112:113], v[112:113], v[118:119]
	v_add_f32_e32 v0, 1.0, v0
	v_rcp_f32_e32 v118, v0
	v_and_b32_e32 v0, 0xffff0000, v120
	v_mul_f32_e32 v0, 0xbfb8aa3b, v0
	v_exp_f32_e32 v0, v0
	s_nop 0
	v_add_f32_e32 v0, 1.0, v0
	v_rcp_f32_e32 v119, v0
	v_lshlrev_b32_e32 v0, 16, v121
	v_mul_f32_e32 v0, 0xbfb8aa3b, v0
	v_exp_f32_e32 v0, v0
	v_pk_mul_f32 v[106:107], v[106:107], v[118:119]
	v_add_f32_e32 v0, 1.0, v0
	v_rcp_f32_e32 v118, v0
	v_and_b32_e32 v0, 0xffff0000, v121
	v_mul_f32_e32 v0, 0xbfb8aa3b, v0
	v_exp_f32_e32 v0, v0
	s_nop 0
	v_add_f32_e32 v0, 1.0, v0
	v_rcp_f32_e32 v119, v0
	s_nop 0
	v_pk_mul_f32 v[108:109], v[108:109], v[118:119]
	s_cbranch_vccnz .LBB0_149
	s_waitcnt vmcnt(5)
	v_mov_b32_e32 v118, v242
	v_mov_b32_e32 v119, v243
	v_mov_b32_e32 v120, v244
	v_mov_b32_e32 v121, v245
	v_lshlrev_b32_e32 v122, 16, v118
	v_and_b32_e32 v123, 0xffff0000, v118
	v_lshlrev_b32_e32 v118, 16, v119
	v_and_b32_e32 v119, 0xffff0000, v119
	v_pk_add_f32 v[112:113], v[112:113], v[118:119]
	v_lshlrev_b32_e32 v118, 16, v120
	v_and_b32_e32 v119, 0xffff0000, v120
	v_pk_add_f32 v[106:107], v[106:107], v[118:119]
	v_lshlrev_b32_e32 v118, 16, v121
	v_and_b32_e32 v119, 0xffff0000, v121
	v_pk_add_f32 v[110:111], v[110:111], v[122:123]
	v_pk_add_f32 v[108:109], v[108:109], v[118:119]
.LBB0_149:
	v_cvt_pk_bf16_f32 v110, v110, v111
	v_cvt_pk_bf16_f32 v111, v112, v113
	v_cvt_pk_bf16_f32 v112, v106, v107
	s_nop 0
	v_cvt_pk_bf16_f32 v113, v108, v109
	global_store_dwordx4 v[114:115], v[110:113], off
	s_and_b64 vcc, exec, s[36:37]
	s_waitcnt vmcnt(6)
	v_mov_b32_e32 v106, v238
	v_mov_b32_e32 v107, v239
	v_mov_b32_e32 v108, v240
	v_mov_b32_e32 v109, v241
	v_lshlrev_b32_e32 v0, 16, v106
	v_and_b32_e32 v106, 0xffff0000, v106
	v_lshlrev_b32_e32 v110, 16, v107
	v_and_b32_e32 v107, 0xffff0000, v107
	v_lshlrev_b32_e32 v111, 16, v108
	v_and_b32_e32 v108, 0xffff0000, v108
	v_lshlrev_b32_e32 v112, 16, v109
	v_and_b32_e32 v109, 0xffff0000, v109
	v_mul_f32_e32 v0, 0xbfb8aa3b, v0
	v_mul_f32_e32 v106, 0xbfb8aa3b, v106
	v_mul_f32_e32 v110, 0xbfb8aa3b, v110
	v_mul_f32_e32 v107, 0xbfb8aa3b, v107
	v_mul_f32_e32 v111, 0xbfb8aa3b, v111
	v_mul_f32_e32 v108, 0xbfb8aa3b, v108
	v_mul_f32_e32 v112, 0xbfb8aa3b, v112
	v_mul_f32_e32 v109, 0xbfb8aa3b, v109
	v_exp_f32_e32 v0, v0
	v_exp_f32_e32 v106, v106
	v_exp_f32_e32 v110, v110
	v_exp_f32_e32 v107, v107
	v_exp_f32_e32 v111, v111
	v_exp_f32_e32 v108, v108
	v_exp_f32_e32 v112, v112
	v_exp_f32_e32 v109, v109
	v_add_f32_e32 v0, 1.0, v0
	v_add_f32_e32 v113, 1.0, v106
	v_add_f32_e32 v110, 1.0, v110
	v_add_f32_e32 v116, 1.0, v107
	v_add_f32_e32 v111, 1.0, v111
	v_add_f32_e32 v117, 1.0, v108
	v_add_f32_e32 v112, 1.0, v112
	v_add_f32_e32 v118, 1.0, v109
	v_rcp_f32_e32 v106, v0
	v_rcp_f32_e32 v107, v113
	v_rcp_f32_e32 v108, v110
	v_rcp_f32_e32 v109, v116
	v_rcp_f32_e32 v110, v111
	v_rcp_f32_e32 v111, v117
	v_rcp_f32_e32 v112, v112
	v_rcp_f32_e32 v113, v118
	v_pk_mul_f32 v[102:103], v[102:103], v[106:107]
	v_pk_mul_f32 v[104:105], v[104:105], v[108:109]
	v_pk_mul_f32 v[106:107], v[98:99], v[110:111]
	v_pk_mul_f32 v[98:99], v[100:101], v[112:113]
	s_cbranch_vccnz .LBB0_151
	s_waitcnt vmcnt(4)
	v_mov_b32_e32 v108, v174
	v_mov_b32_e32 v109, v175
	v_mov_b32_e32 v110, v176
	v_mov_b32_e32 v111, v177
	v_lshlrev_b32_e32 v100, 16, v108
	v_and_b32_e32 v101, 0xffff0000, v108
	v_pk_add_f32 v[102:103], v[102:103], v[100:101]
	v_lshlrev_b32_e32 v100, 16, v109
	v_and_b32_e32 v101, 0xffff0000, v109
	v_pk_add_f32 v[104:105], v[104:105], v[100:101]
	v_lshlrev_b32_e32 v100, 16, v110
	v_and_b32_e32 v101, 0xffff0000, v110
	v_pk_add_f32 v[106:107], v[106:107], v[100:101]
	v_lshlrev_b32_e32 v100, 16, v111
	v_and_b32_e32 v101, 0xffff0000, v111
	v_pk_add_f32 v[98:99], v[98:99], v[100:101]
; DI float bflo(unsigned w) { return __uint_as_float(w << 16); }
; DI float bfhi(unsigned w) { return __uint_as_float(w & 0xffff0000u); }
; DI unsigned cvtpk(float lo, float hi) { unsigned r; asm volatile("v_cvt_pk_bf16_f32 %0, %1, %2" : "=v"(r) : "v"(lo), "v"(hi)); return r; }
; DI float sigmoidf_(float x) { return __builtin_amdgcn_rcpf(1.f + __expf(-x)); }
;     __device__ __forceinline__ void operator()(const f32x4 (&acc)[2][2][4][2], const Unit& u, int wr, int wc, int fr, int fq) const {
;     ...
;                 const int row = u.pm * BM + ai * HALF + wr * 64 + m * 16 + fr;
;                 const int colb = pn * BM + wc * 32 + 8 * fq;
;                 const unsigned goff = (unsigned)(row * LDP + C_GT + br * 1024 + colb), ooff = (unsigned)(row * 1024 + colb);
;                 const bf16_t* gp = proj + goff;
;                 bf16_t* op = out + ooff;
;                 __builtin_amdgcn_sched_barrier(0);
; #pragma unroll
;                 for (int bj = 0; bj < 2; ++bj) {
;                     const u32x4 g = *(const u32x4*)(gp + bj * HALF);
;                     f32x4 v0 = acc[ai][bj][m][0], v1 = acc[ai][bj][m][1];
;                     v0[0] *= sigmoidf_(bflo(g[0])); v0[1] *= sigmoidf_(bfhi(g[0])); v0[2] *= sigmoidf_(bflo(g[1])); v0[3] *= sigmoidf_(bfhi(g[1]));
;                     v1[0] *= sigmoidf_(bflo(g[2])); v1[1] *= sigmoidf_(bfhi(g[2])); v1[2] *= sigmoidf_(bflo(g[3])); v1[3] *= sigmoidf_(bfhi(g[3]));
;                     if (br > 0) {
;                         const u32x4 o = *(const u32x4*)(op + bj * HALF);
;                         v0[0] += bflo(o[0]); v0[1] += bfhi(o[0]); v0[2] += bflo(o[1]); v0[3] += bfhi(o[1]);
;                         v1[0] += bflo(o[2]); v1[1] += bfhi(o[2]); v1[2] += bflo(o[3]); v1[3] += bfhi(o[3]);
;                     }
;                     u32x4 w = {cvtpk(v0[0], v0[1]), cvtpk(v0[2], v0[3]), cvtpk(v1[0], v1[1]), cvtpk(v1[2], v1[3])};
;                     *(u32x4*)(op + bj * HALF) = w;
.LBB0_151:
	v_readlane_b32 s80, v255, 8
	v_cvt_pk_bf16_f32 v100, v102, v103
	v_cvt_pk_bf16_f32 v101, v104, v105
	v_cvt_pk_bf16_f32 v102, v106, v107
	v_cvt_pk_bf16_f32 v103, v98, v99
	v_add_u32_e32 v0, v167, v151
	v_or_b32_e32 v98, v166, v152
	v_readlane_b32 s92, v255, 20
	v_readlane_b32 s93, v255, 21
	v_readlane_b32 s94, v255, 22
	v_readlane_b32 s95, v255, 23
	v_mov_b32_e32 v99, v1
	global_store_dwordx4 v[114:115], v[100:103], off offset:256
	v_lshl_add_u64 v[98:99], v[98:99], 1, s[92:93]
	v_readlane_b32 s81, v255, 9
	v_lshl_add_u64 v[100:101], v[0:1], 1, s[94:95]
	v_readlane_b32 s82, v255, 10
	v_readlane_b32 s83, v255, 11
	v_readlane_b32 s84, v255, 12
	v_readlane_b32 s85, v255, 13
	v_readlane_b32 s86, v255, 14
	v_readlane_b32 s87, v255, 15
	v_readlane_b32 s88, v255, 16
	v_readlane_b32 s89, v255, 17
	v_readlane_b32 s90, v255, 18
	v_readlane_b32 s91, v255, 19
	v_add_u32_e32 v178, v167, v153
	v_mov_b32_e32 v179, v1
	v_lshl_add_u64 v[178:179], v[178:179], 1, s[94:95]
	v_or_b32_e32 v180, v166, v154
	v_mov_b32_e32 v181, v1
	v_lshl_add_u64 v[180:181], v[180:181], 1, s[92:93]
	global_load_dwordx4 v[234:237], v[178:179], off
	global_load_dwordx4 v[238:241], v[178:179], off offset:256
	global_load_dwordx4 v[242:245], v[180:181], off
	global_load_dwordx4 v[174:177], v[180:181], off offset:256
	s_and_b64 vcc, exec, s[36:37]
	s_waitcnt vmcnt(7)
	v_mov_b32_e32 v102, v218
	v_mov_b32_e32 v103, v219
	v_mov_b32_e32 v104, v220
	v_mov_b32_e32 v105, v221
	v_lshlrev_b32_e32 v0, 16, v102
	v_mul_f32_e32 v0, 0xbfb8aa3b, v0
	v_exp_f32_e32 v0, v0
	s_nop 0
	v_add_f32_e32 v0, 1.0, v0
	v_rcp_f32_e32 v106, v0
	v_and_b32_e32 v0, 0xffff0000, v102
	v_mul_f32_e32 v0, 0xbfb8aa3b, v0
	v_exp_f32_e32 v0, v0
	s_nop 0
	v_add_f32_e32 v0, 1.0, v0
	v_rcp_f32_e32 v107, v0
	v_lshlrev_b32_e32 v0, 16, v103
	v_mul_f32_e32 v0, 0xbfb8aa3b, v0
	v_exp_f32_e32 v0, v0
	v_pk_mul_f32 v[94:95], v[94:95], v[106:107]
	v_add_f32_e32 v0, 1.0, v0
	v_rcp_f32_e32 v102, v0
	v_and_b32_e32 v0, 0xffff0000, v103
	v_mul_f32_e32 v0, 0xbfb8aa3b, v0
	v_exp_f32_e32 v0, v0
	s_nop 0
	v_add_f32_e32 v0, 1.0, v0
	v_rcp_f32_e32 v103, v0
	v_lshlrev_b32_e32 v0, 16, v104
	v_mul_f32_e32 v0, 0xbfb8aa3b, v0
	v_exp_f32_e32 v0, v0
	v_pk_mul_f32 v[96:97], v[96:97], v[102:103]
	v_add_f32_e32 v0, 1.0, v0
	v_rcp_f32_e32 v102, v0
	v_and_b32_e32 v0, 0xffff0000, v104
	v_mul_f32_e32 v0, 0xbfb8aa3b, v0
	v_exp_f32_e32 v0, v0
	s_nop 0
	v_add_f32_e32 v0, 1.0, v0
	v_rcp_f32_e32 v103, v0
	v_lshlrev_b32_e32 v0, 16, v105
	v_mul_f32_e32 v0, 0xbfb8aa3b, v0
	v_exp_f32_e32 v0, v0
	v_pk_mul_f32 v[90:91], v[90:91], v[102:103]
	v_add_f32_e32 v0, 1.0, v0
	v_rcp_f32_e32 v102, v0
	v_and_b32_e32 v0, 0xffff0000, v105
	v_mul_f32_e32 v0, 0xbfb8aa3b, v0
	v_exp_f32_e32 v0, v0
	s_nop 0
	v_add_f32_e32 v0, 1.0, v0
	v_rcp_f32_e32 v103, v0
	s_nop 0
	v_pk_mul_f32 v[92:93], v[92:93], v[102:103]
	s_cbranch_vccnz .LBB0_153
	s_waitcnt vmcnt(5)
	v_mov_b32_e32 v102, v226
	v_mov_b32_e32 v103, v227
	v_mov_b32_e32 v104, v228
	v_mov_b32_e32 v105, v229
	v_lshlrev_b32_e32 v106, 16, v102
	v_and_b32_e32 v107, 0xffff0000, v102
	v_lshlrev_b32_e32 v102, 16, v103
	v_and_b32_e32 v103, 0xffff0000, v103
	v_pk_add_f32 v[96:97], v[96:97], v[102:103]
	v_lshlrev_b32_e32 v102, 16, v104
	v_and_b32_e32 v103, 0xffff0000, v104
	v_pk_add_f32 v[90:91], v[90:91], v[102:103]
	v_lshlrev_b32_e32 v102, 16, v105
	v_and_b32_e32 v103, 0xffff0000, v105
	v_pk_add_f32 v[94:95], v[94:95], v[106:107]
	v_pk_add_f32 v[92:93], v[92:93], v[102:103]
.LBB0_153:
	v_cvt_pk_bf16_f32 v94, v94, v95
	v_cvt_pk_bf16_f32 v95, v96, v97
	v_cvt_pk_bf16_f32 v96, v90, v91
	s_nop 0
	v_cvt_pk_bf16_f32 v97, v92, v93
	global_store_dwordx4 v[98:99], v[94:97], off
	s_and_b64 vcc, exec, s[36:37]
	s_waitcnt vmcnt(6)
	v_mov_b32_e32 v90, v222
	v_mov_b32_e32 v91, v223
	v_mov_b32_e32 v92, v224
	v_mov_b32_e32 v93, v225
	v_lshlrev_b32_e32 v0, 16, v90
	v_and_b32_e32 v90, 0xffff0000, v90
	v_lshlrev_b32_e32 v94, 16, v91
	v_and_b32_e32 v91, 0xffff0000, v91
	v_lshlrev_b32_e32 v95, 16, v92
	v_and_b32_e32 v92, 0xffff0000, v92
	v_lshlrev_b32_e32 v96, 16, v93
	v_and_b32_e32 v93, 0xffff0000, v93
	v_mul_f32_e32 v0, 0xbfb8aa3b, v0
	v_mul_f32_e32 v90, 0xbfb8aa3b, v90
	v_mul_f32_e32 v94, 0xbfb8aa3b, v94
	v_mul_f32_e32 v91, 0xbfb8aa3b, v91
	v_mul_f32_e32 v95, 0xbfb8aa3b, v95
	v_mul_f32_e32 v92, 0xbfb8aa3b, v92
	v_mul_f32_e32 v96, 0xbfb8aa3b, v96
	v_mul_f32_e32 v93, 0xbfb8aa3b, v93
	v_exp_f32_e32 v0, v0
	v_exp_f32_e32 v90, v90
	v_exp_f32_e32 v94, v94
	v_exp_f32_e32 v91, v91
	v_exp_f32_e32 v95, v95
	v_exp_f32_e32 v92, v92
	v_exp_f32_e32 v96, v96
	v_exp_f32_e32 v93, v93
	v_add_f32_e32 v0, 1.0, v0
	v_add_f32_e32 v97, 1.0, v90
	v_add_f32_e32 v94, 1.0, v94
	v_add_f32_e32 v100, 1.0, v91
	v_add_f32_e32 v95, 1.0, v95
	v_add_f32_e32 v101, 1.0, v92
	v_add_f32_e32 v96, 1.0, v96
	v_add_f32_e32 v102, 1.0, v93
	v_rcp_f32_e32 v90, v0
	v_rcp_f32_e32 v91, v97
	v_rcp_f32_e32 v92, v94
	v_rcp_f32_e32 v93, v100
	v_rcp_f32_e32 v94, v95
	v_rcp_f32_e32 v95, v101
	v_rcp_f32_e32 v96, v96
	v_rcp_f32_e32 v97, v102
	v_pk_mul_f32 v[86:87], v[86:87], v[90:91]
	v_pk_mul_f32 v[88:89], v[88:89], v[92:93]
	v_pk_mul_f32 v[90:91], v[82:83], v[94:95]
	v_pk_mul_f32 v[82:83], v[84:85], v[96:97]
	s_cbranch_vccnz .LBB0_155
	s_waitcnt vmcnt(4)
	v_mov_b32_e32 v92, v230
	v_mov_b32_e32 v93, v231
	v_mov_b32_e32 v94, v232
	v_mov_b32_e32 v95, v233
	v_lshlrev_b32_e32 v84, 16, v92
	v_and_b32_e32 v85, 0xffff0000, v92
	v_pk_add_f32 v[86:87], v[86:87], v[84:85]
	v_lshlrev_b32_e32 v84, 16, v93
	v_and_b32_e32 v85, 0xffff0000, v93
	v_pk_add_f32 v[88:89], v[88:89], v[84:85]
	v_lshlrev_b32_e32 v84, 16, v94
	v_and_b32_e32 v85, 0xffff0000, v94
	v_pk_add_f32 v[90:91], v[90:91], v[84:85]
	v_lshlrev_b32_e32 v84, 16, v95
	v_and_b32_e32 v85, 0xffff0000, v95
	v_pk_add_f32 v[82:83], v[82:83], v[84:85]
; DI float bflo(unsigned w) { return __uint_as_float(w << 16); }
; DI float bfhi(unsigned w) { return __uint_as_float(w & 0xffff0000u); }
; DI unsigned cvtpk(float lo, float hi) { unsigned r; asm volatile("v_cvt_pk_bf16_f32 %0, %1, %2" : "=v"(r) : "v"(lo), "v"(hi)); return r; }
; DI float sigmoidf_(float x) { return __builtin_amdgcn_rcpf(1.f + __expf(-x)); }
;     __device__ __forceinline__ void operator()(const f32x4 (&acc)[2][2][4][2], const Unit& u, int wr, int wc, int fr, int fq) const {
;     ...
;                 const int row = u.pm * BM + ai * HALF + wr * 64 + m * 16 + fr;
;                 const int colb = pn * BM + wc * 32 + 8 * fq;
;                 const unsigned goff = (unsigned)(row * LDP + C_GT + br * 1024 + colb), ooff = (unsigned)(row * 1024 + colb);
;                 const bf16_t* gp = proj + goff;
;                 bf16_t* op = out + ooff;
;                 __builtin_amdgcn_sched_barrier(0);
; #pragma unroll
;                 for (int bj = 0; bj < 2; ++bj) {
;                     const u32x4 g = *(const u32x4*)(gp + bj * HALF);
;                     f32x4 v0 = acc[ai][bj][m][0], v1 = acc[ai][bj][m][1];
;                     v0[0] *= sigmoidf_(bflo(g[0])); v0[1] *= sigmoidf_(bfhi(g[0])); v0[2] *= sigmoidf_(bflo(g[1])); v0[3] *= sigmoidf_(bfhi(g[1]));
;                     v1[0] *= sigmoidf_(bflo(g[2])); v1[1] *= sigmoidf_(bfhi(g[2])); v1[2] *= sigmoidf_(bflo(g[3])); v1[3] *= sigmoidf_(bfhi(g[3]));
;                     if (br > 0) {
;                         const u32x4 o = *(const u32x4*)(op + bj * HALF);
;                         v0[0] += bflo(o[0]); v0[1] += bfhi(o[0]); v0[2] += bflo(o[1]); v0[3] += bfhi(o[1]);
;                         v1[0] += bflo(o[2]); v1[1] += bfhi(o[2]); v1[2] += bflo(o[3]); v1[3] += bfhi(o[3]);
;                     }
;                     u32x4 w = {cvtpk(v0[0], v0[1]), cvtpk(v0[2], v0[3]), cvtpk(v1[0], v1[1]), cvtpk(v1[2], v1[3])};
;                     *(u32x4*)(op + bj * HALF) = w;
.LBB0_155:
	v_readlane_b32 s80, v255, 8
	v_cvt_pk_bf16_f32 v84, v86, v87
	v_cvt_pk_bf16_f32 v85, v88, v89
	v_cvt_pk_bf16_f32 v86, v90, v91
	v_cvt_pk_bf16_f32 v87, v82, v83
	v_add_u32_e32 v0, v167, v153
	v_or_b32_e32 v82, v166, v154
	v_readlane_b32 s92, v255, 20
	v_readlane_b32 s93, v255, 21
	v_readlane_b32 s94, v255, 22
	v_readlane_b32 s95, v255, 23
	v_mov_b32_e32 v83, v1
	global_store_dwordx4 v[98:99], v[84:87], off offset:256
	v_lshl_add_u64 v[82:83], v[82:83], 1, s[92:93]
	v_readlane_b32 s81, v255, 9
	v_lshl_add_u64 v[84:85], v[0:1], 1, s[94:95]
	v_readlane_b32 s82, v255, 10
	v_readlane_b32 s83, v255, 11
	v_readlane_b32 s84, v255, 12
	v_readlane_b32 s85, v255, 13
	v_readlane_b32 s86, v255, 14
	v_readlane_b32 s87, v255, 15
	v_readlane_b32 s88, v255, 16
	v_readlane_b32 s89, v255, 17
	v_readlane_b32 s90, v255, 18
	v_readlane_b32 s91, v255, 19
	v_add_u32_e32 v178, v167, v155
	v_mov_b32_e32 v179, v1
	v_lshl_add_u64 v[178:179], v[178:179], 1, s[94:95]
	v_or_b32_e32 v180, v166, v157
	v_mov_b32_e32 v181, v1
	v_lshl_add_u64 v[180:181], v[180:181], 1, s[92:93]
	global_load_dwordx4 v[218:221], v[178:179], off
	global_load_dwordx4 v[222:225], v[178:179], off offset:256
	global_load_dwordx4 v[226:229], v[180:181], off
	global_load_dwordx4 v[230:233], v[180:181], off offset:256
	s_and_b64 vcc, exec, s[36:37]
	s_waitcnt vmcnt(7)
	v_mov_b32_e32 v86, v234
	v_mov_b32_e32 v87, v235
	v_mov_b32_e32 v88, v236
	v_mov_b32_e32 v89, v237
	v_lshlrev_b32_e32 v0, 16, v86
	v_mul_f32_e32 v0, 0xbfb8aa3b, v0
	v_exp_f32_e32 v0, v0
	s_nop 0
	v_add_f32_e32 v0, 1.0, v0
	v_rcp_f32_e32 v90, v0
	v_and_b32_e32 v0, 0xffff0000, v86
	v_mul_f32_e32 v0, 0xbfb8aa3b, v0
	v_exp_f32_e32 v0, v0
	s_nop 0
	v_add_f32_e32 v0, 1.0, v0
	v_rcp_f32_e32 v91, v0
	v_lshlrev_b32_e32 v0, 16, v87
	v_mul_f32_e32 v0, 0xbfb8aa3b, v0
	v_exp_f32_e32 v0, v0
	v_pk_mul_f32 v[78:79], v[78:79], v[90:91]
	v_add_f32_e32 v0, 1.0, v0
	v_rcp_f32_e32 v86, v0
	v_and_b32_e32 v0, 0xffff0000, v87
	v_mul_f32_e32 v0, 0xbfb8aa3b, v0
	v_exp_f32_e32 v0, v0
	s_nop 0
	v_add_f32_e32 v0, 1.0, v0
	v_rcp_f32_e32 v87, v0
	v_lshlrev_b32_e32 v0, 16, v88
	v_mul_f32_e32 v0, 0xbfb8aa3b, v0
	v_exp_f32_e32 v0, v0
	v_pk_mul_f32 v[80:81], v[80:81], v[86:87]
	v_add_f32_e32 v0, 1.0, v0
	v_rcp_f32_e32 v86, v0
	v_and_b32_e32 v0, 0xffff0000, v88
	v_mul_f32_e32 v0, 0xbfb8aa3b, v0
	v_exp_f32_e32 v0, v0
	s_nop 0
	v_add_f32_e32 v0, 1.0, v0
	v_rcp_f32_e32 v87, v0
	v_lshlrev_b32_e32 v0, 16, v89
	v_mul_f32_e32 v0, 0xbfb8aa3b, v0
	v_exp_f32_e32 v0, v0
	v_pk_mul_f32 v[74:75], v[74:75], v[86:87]
	v_add_f32_e32 v0, 1.0, v0
	v_rcp_f32_e32 v86, v0
	v_and_b32_e32 v0, 0xffff0000, v89
	v_mul_f32_e32 v0, 0xbfb8aa3b, v0
	v_exp_f32_e32 v0, v0
	s_nop 0
	v_add_f32_e32 v0, 1.0, v0
	v_rcp_f32_e32 v87, v0
	s_nop 0
	v_pk_mul_f32 v[76:77], v[76:77], v[86:87]
	s_cbranch_vccnz .LBB0_157
	s_waitcnt vmcnt(5)
	v_mov_b32_e32 v86, v242
	v_mov_b32_e32 v87, v243
	v_mov_b32_e32 v88, v244
	v_mov_b32_e32 v89, v245
	v_lshlrev_b32_e32 v90, 16, v86
	v_and_b32_e32 v91, 0xffff0000, v86
	v_lshlrev_b32_e32 v86, 16, v87
	v_and_b32_e32 v87, 0xffff0000, v87
	v_pk_add_f32 v[80:81], v[80:81], v[86:87]
	v_lshlrev_b32_e32 v86, 16, v88
	v_and_b32_e32 v87, 0xffff0000, v88
	v_pk_add_f32 v[74:75], v[74:75], v[86:87]
	v_lshlrev_b32_e32 v86, 16, v89
	v_and_b32_e32 v87, 0xffff0000, v89
	v_pk_add_f32 v[78:79], v[78:79], v[90:91]
	v_pk_add_f32 v[76:77], v[76:77], v[86:87]
.LBB0_157:
	v_cvt_pk_bf16_f32 v78, v78, v79
	v_cvt_pk_bf16_f32 v79, v80, v81
	v_cvt_pk_bf16_f32 v80, v74, v75
	s_nop 0
	v_cvt_pk_bf16_f32 v81, v76, v77
	global_store_dwordx4 v[82:83], v[78:81], off
	s_and_b64 vcc, exec, s[36:37]
	s_waitcnt vmcnt(6)
	v_mov_b32_e32 v74, v238
	v_mov_b32_e32 v75, v239
	v_mov_b32_e32 v76, v240
	v_mov_b32_e32 v77, v241
	v_lshlrev_b32_e32 v0, 16, v74
	v_and_b32_e32 v74, 0xffff0000, v74
	v_lshlrev_b32_e32 v78, 16, v75
	v_and_b32_e32 v75, 0xffff0000, v75
	v_lshlrev_b32_e32 v79, 16, v76
	v_and_b32_e32 v76, 0xffff0000, v76
	v_lshlrev_b32_e32 v80, 16, v77
	v_and_b32_e32 v77, 0xffff0000, v77
	v_mul_f32_e32 v0, 0xbfb8aa3b, v0
	v_mul_f32_e32 v74, 0xbfb8aa3b, v74
	v_mul_f32_e32 v78, 0xbfb8aa3b, v78
	v_mul_f32_e32 v75, 0xbfb8aa3b, v75
	v_mul_f32_e32 v79, 0xbfb8aa3b, v79
	v_mul_f32_e32 v76, 0xbfb8aa3b, v76
	v_mul_f32_e32 v80, 0xbfb8aa3b, v80
	v_mul_f32_e32 v77, 0xbfb8aa3b, v77
	v_exp_f32_e32 v0, v0
	v_exp_f32_e32 v74, v74
	v_exp_f32_e32 v78, v78
	v_exp_f32_e32 v75, v75
	v_exp_f32_e32 v79, v79
	v_exp_f32_e32 v76, v76
	v_exp_f32_e32 v80, v80
	v_exp_f32_e32 v77, v77
	v_add_f32_e32 v0, 1.0, v0
	v_add_f32_e32 v81, 1.0, v74
	v_add_f32_e32 v78, 1.0, v78
	v_add_f32_e32 v84, 1.0, v75
	v_add_f32_e32 v79, 1.0, v79
	v_add_f32_e32 v85, 1.0, v76
	v_add_f32_e32 v80, 1.0, v80
	v_add_f32_e32 v86, 1.0, v77
	v_rcp_f32_e32 v74, v0
	v_rcp_f32_e32 v75, v81
	v_rcp_f32_e32 v76, v78
	v_rcp_f32_e32 v77, v84
	v_rcp_f32_e32 v78, v79
	v_rcp_f32_e32 v79, v85
	v_rcp_f32_e32 v80, v80
	v_rcp_f32_e32 v81, v86
	v_pk_mul_f32 v[70:71], v[70:71], v[74:75]
	v_pk_mul_f32 v[72:73], v[72:73], v[76:77]
	v_pk_mul_f32 v[74:75], v[66:67], v[78:79]
	v_pk_mul_f32 v[66:67], v[68:69], v[80:81]
	s_cbranch_vccnz .LBB0_159
	s_waitcnt vmcnt(4)
	v_mov_b32_e32 v76, v174
	v_mov_b32_e32 v77, v175
	v_mov_b32_e32 v78, v176
	v_mov_b32_e32 v79, v177
	v_lshlrev_b32_e32 v68, 16, v76
	v_and_b32_e32 v69, 0xffff0000, v76
	v_pk_add_f32 v[70:71], v[70:71], v[68:69]
	v_lshlrev_b32_e32 v68, 16, v77
	v_and_b32_e32 v69, 0xffff0000, v77
	v_pk_add_f32 v[72:73], v[72:73], v[68:69]
	v_lshlrev_b32_e32 v68, 16, v78
	v_and_b32_e32 v69, 0xffff0000, v78
	v_pk_add_f32 v[74:75], v[74:75], v[68:69]
	v_lshlrev_b32_e32 v68, 16, v79
	v_and_b32_e32 v69, 0xffff0000, v79
	v_pk_add_f32 v[66:67], v[66:67], v[68:69]
; DI float bflo(unsigned w) { return __uint_as_float(w << 16); }
; DI float bfhi(unsigned w) { return __uint_as_float(w & 0xffff0000u); }
; DI unsigned cvtpk(float lo, float hi) { unsigned r; asm volatile("v_cvt_pk_bf16_f32 %0, %1, %2" : "=v"(r) : "v"(lo), "v"(hi)); return r; }
; DI float sigmoidf_(float x) { return __builtin_amdgcn_rcpf(1.f + __expf(-x)); }
;     __device__ __forceinline__ void operator()(const f32x4 (&acc)[2][2][4][2], const Unit& u, int wr, int wc, int fr, int fq) const {
;     ...
;             for (int m = 0; m < 4; ++m) {
;                 const int row = u.pm * BM + ai * HALF + wr * 64 + m * 16 + fr;
;                 const int colb = pn * BM + wc * 32 + 8 * fq;
;                 const unsigned goff = (unsigned)(row * LDP + C_GT + br * 1024 + colb), ooff = (unsigned)(row * 1024 + colb);
;                 const bf16_t* gp = proj + goff;
;                 bf16_t* op = out + ooff;
;                 __builtin_amdgcn_sched_barrier(0);
; #pragma unroll
;                 for (int bj = 0; bj < 2; ++bj) {
;                     const u32x4 g = *(const u32x4*)(gp + bj * HALF);
;                     f32x4 v0 = acc[ai][bj][m][0], v1 = acc[ai][bj][m][1];
;                     v0[0] *= sigmoidf_(bflo(g[0])); v0[1] *= sigmoidf_(bfhi(g[0])); v0[2] *= sigmoidf_(bflo(g[1])); v0[3] *= sigmoidf_(bfhi(g[1]));
;                     v1[0] *= sigmoidf_(bflo(g[2])); v1[1] *= sigmoidf_(bfhi(g[2])); v1[2] *= sigmoidf_(bflo(g[3])); v1[3] *= sigmoidf_(bfhi(g[3]));
;                     if (br > 0) {
;                         const u32x4 o = *(const u32x4*)(op + bj * HALF);
;                         v0[0] += bflo(o[0]); v0[1] += bfhi(o[0]); v0[2] += bflo(o[1]); v0[3] += bfhi(o[1]);
;                         v1[0] += bflo(o[2]); v1[1] += bfhi(o[2]); v1[2] += bflo(o[3]); v1[3] += bfhi(o[3]);
;                     }
;                     u32x4 w = {cvtpk(v0[0], v0[1]), cvtpk(v0[2], v0[3]), cvtpk(v1[0], v1[1]), cvtpk(v1[2], v1[3])};
;                     *(u32x4*)(op + bj * HALF) = w;
;                 }
.LBB0_159:
	v_readlane_b32 s80, v255, 8
	v_cvt_pk_bf16_f32 v68, v70, v71
	v_cvt_pk_bf16_f32 v69, v72, v73
	v_cvt_pk_bf16_f32 v70, v74, v75
	v_cvt_pk_bf16_f32 v71, v66, v67
	v_add_u32_e32 v0, v167, v155
	v_or_b32_e32 v66, v166, v157
	v_readlane_b32 s92, v255, 20
	v_readlane_b32 s93, v255, 21
	v_readlane_b32 s94, v255, 22
	v_readlane_b32 s95, v255, 23
	v_mov_b32_e32 v67, v1
	global_store_dwordx4 v[82:83], v[68:71], off offset:256
	v_lshl_add_u64 v[66:67], v[66:67], 1, s[92:93]
	v_readlane_b32 s81, v255, 9
	v_lshl_add_u64 v[68:69], v[0:1], 1, s[94:95]
	v_readlane_b32 s82, v255, 10
	v_readlane_b32 s83, v255, 11
	v_readlane_b32 s84, v255, 12
	v_readlane_b32 s85, v255, 13
	v_readlane_b32 s86, v255, 14
	v_readlane_b32 s87, v255, 15
	v_readlane_b32 s88, v255, 16
	v_readlane_b32 s89, v255, 17
	v_readlane_b32 s90, v255, 18
	v_readlane_b32 s91, v255, 19
	v_add_u32_e32 v178, v167, v158
	v_mov_b32_e32 v179, v1
	v_lshl_add_u64 v[178:179], v[178:179], 1, s[94:95]
	v_or_b32_e32 v180, v166, v159
	v_mov_b32_e32 v181, v1
	v_lshl_add_u64 v[180:181], v[180:181], 1, s[92:93]
	global_load_dwordx4 v[234:237], v[178:179], off
	global_load_dwordx4 v[238:241], v[178:179], off offset:256
	global_load_dwordx4 v[242:245], v[180:181], off
	global_load_dwordx4 v[174:177], v[180:181], off offset:256
	s_and_b64 vcc, exec, s[36:37]
	s_waitcnt vmcnt(7)
	v_mov_b32_e32 v70, v218
	v_mov_b32_e32 v71, v219
	v_mov_b32_e32 v72, v220
	v_mov_b32_e32 v73, v221
	v_lshlrev_b32_e32 v0, 16, v70
	v_mul_f32_e32 v0, 0xbfb8aa3b, v0
	v_exp_f32_e32 v0, v0
	s_nop 0
	v_add_f32_e32 v0, 1.0, v0
	v_rcp_f32_e32 v74, v0
	v_and_b32_e32 v0, 0xffff0000, v70
	v_mul_f32_e32 v0, 0xbfb8aa3b, v0
	v_exp_f32_e32 v0, v0
	s_nop 0
	v_add_f32_e32 v0, 1.0, v0
	v_rcp_f32_e32 v75, v0
	v_lshlrev_b32_e32 v0, 16, v71
	v_mul_f32_e32 v0, 0xbfb8aa3b, v0
	v_exp_f32_e32 v0, v0
	v_pk_mul_f32 v[62:63], v[62:63], v[74:75]
	v_add_f32_e32 v0, 1.0, v0
	v_rcp_f32_e32 v70, v0
	v_and_b32_e32 v0, 0xffff0000, v71
	v_mul_f32_e32 v0, 0xbfb8aa3b, v0
	v_exp_f32_e32 v0, v0
	s_nop 0
	v_add_f32_e32 v0, 1.0, v0
	v_rcp_f32_e32 v71, v0
	v_lshlrev_b32_e32 v0, 16, v72
	v_mul_f32_e32 v0, 0xbfb8aa3b, v0
	v_exp_f32_e32 v0, v0
	v_pk_mul_f32 v[64:65], v[64:65], v[70:71]
	v_add_f32_e32 v0, 1.0, v0
	v_rcp_f32_e32 v70, v0
	v_and_b32_e32 v0, 0xffff0000, v72
	v_mul_f32_e32 v0, 0xbfb8aa3b, v0
	v_exp_f32_e32 v0, v0
	s_nop 0
	v_add_f32_e32 v0, 1.0, v0
	v_rcp_f32_e32 v71, v0
	v_lshlrev_b32_e32 v0, 16, v73
	v_mul_f32_e32 v0, 0xbfb8aa3b, v0
	v_exp_f32_e32 v0, v0
	v_pk_mul_f32 v[58:59], v[58:59], v[70:71]
	v_add_f32_e32 v0, 1.0, v0
	v_rcp_f32_e32 v70, v0
	v_and_b32_e32 v0, 0xffff0000, v73
	v_mul_f32_e32 v0, 0xbfb8aa3b, v0
	v_exp_f32_e32 v0, v0
	s_nop 0
	v_add_f32_e32 v0, 1.0, v0
	v_rcp_f32_e32 v71, v0
	s_nop 0
	v_pk_mul_f32 v[60:61], v[60:61], v[70:71]
	s_cbranch_vccnz .LBB0_161
	s_waitcnt vmcnt(5)
	v_mov_b32_e32 v70, v226
	v_mov_b32_e32 v71, v227
	v_mov_b32_e32 v72, v228
	v_mov_b32_e32 v73, v229
	v_lshlrev_b32_e32 v74, 16, v70
	v_and_b32_e32 v75, 0xffff0000, v70
	v_lshlrev_b32_e32 v70, 16, v71
	v_and_b32_e32 v71, 0xffff0000, v71
	v_pk_add_f32 v[64:65], v[64:65], v[70:71]
	v_lshlrev_b32_e32 v70, 16, v72
	v_and_b32_e32 v71, 0xffff0000, v72
	v_pk_add_f32 v[58:59], v[58:59], v[70:71]
	v_lshlrev_b32_e32 v70, 16, v73
	v_and_b32_e32 v71, 0xffff0000, v73
	v_pk_add_f32 v[62:63], v[62:63], v[74:75]
	v_pk_add_f32 v[60:61], v[60:61], v[70:71]
.LBB0_161:
	v_cvt_pk_bf16_f32 v62, v62, v63
	v_cvt_pk_bf16_f32 v63, v64, v65
	v_cvt_pk_bf16_f32 v64, v58, v59
	s_nop 0
	v_cvt_pk_bf16_f32 v65, v60, v61
	global_store_dwordx4 v[66:67], v[62:65], off
	s_and_b64 vcc, exec, s[36:37]
	s_waitcnt vmcnt(6)
	v_mov_b32_e32 v58, v222
	v_mov_b32_e32 v59, v223
	v_mov_b32_e32 v60, v224
	v_mov_b32_e32 v61, v225
	v_lshlrev_b32_e32 v0, 16, v58
	v_and_b32_e32 v58, 0xffff0000, v58
	v_lshlrev_b32_e32 v62, 16, v59
	v_and_b32_e32 v59, 0xffff0000, v59
	v_lshlrev_b32_e32 v63, 16, v60
	v_and_b32_e32 v60, 0xffff0000, v60
	v_lshlrev_b32_e32 v64, 16, v61
	v_and_b32_e32 v61, 0xffff0000, v61
	v_mul_f32_e32 v0, 0xbfb8aa3b, v0
	v_mul_f32_e32 v58, 0xbfb8aa3b, v58
	v_mul_f32_e32 v62, 0xbfb8aa3b, v62
	v_mul_f32_e32 v59, 0xbfb8aa3b, v59
	v_mul_f32_e32 v63, 0xbfb8aa3b, v63
	v_mul_f32_e32 v60, 0xbfb8aa3b, v60
	v_mul_f32_e32 v64, 0xbfb8aa3b, v64
	v_mul_f32_e32 v61, 0xbfb8aa3b, v61
	v_exp_f32_e32 v0, v0
	v_exp_f32_e32 v58, v58
	v_exp_f32_e32 v62, v62
	v_exp_f32_e32 v59, v59
	v_exp_f32_e32 v63, v63
	v_exp_f32_e32 v60, v60
	v_exp_f32_e32 v64, v64
	v_exp_f32_e32 v61, v61
	v_add_f32_e32 v0, 1.0, v0
	v_add_f32_e32 v65, 1.0, v58
	v_add_f32_e32 v62, 1.0, v62
	v_add_f32_e32 v68, 1.0, v59
	v_add_f32_e32 v63, 1.0, v63
	v_add_f32_e32 v69, 1.0, v60
	v_add_f32_e32 v64, 1.0, v64
	v_add_f32_e32 v70, 1.0, v61
	v_rcp_f32_e32 v58, v0
	v_rcp_f32_e32 v59, v65
	v_rcp_f32_e32 v60, v62
	v_rcp_f32_e32 v61, v68
	v_rcp_f32_e32 v62, v63
	v_rcp_f32_e32 v63, v69
	v_rcp_f32_e32 v64, v64
	v_rcp_f32_e32 v65, v70
	v_pk_mul_f32 v[54:55], v[54:55], v[58:59]
	v_pk_mul_f32 v[56:57], v[56:57], v[60:61]
	v_pk_mul_f32 v[58:59], v[50:51], v[62:63]
	v_pk_mul_f32 v[50:51], v[52:53], v[64:65]
	s_cbranch_vccnz .LBB0_163
	s_waitcnt vmcnt(4)
	v_mov_b32_e32 v60, v230
	v_mov_b32_e32 v61, v231
	v_mov_b32_e32 v62, v232
	v_mov_b32_e32 v63, v233
	v_lshlrev_b32_e32 v52, 16, v60
	v_and_b32_e32 v53, 0xffff0000, v60
	v_pk_add_f32 v[54:55], v[54:55], v[52:53]
	v_lshlrev_b32_e32 v52, 16, v61
	v_and_b32_e32 v53, 0xffff0000, v61
	v_pk_add_f32 v[56:57], v[56:57], v[52:53]
	v_lshlrev_b32_e32 v52, 16, v62
	v_and_b32_e32 v53, 0xffff0000, v62
	v_pk_add_f32 v[58:59], v[58:59], v[52:53]
	v_lshlrev_b32_e32 v52, 16, v63
	v_and_b32_e32 v53, 0xffff0000, v63
	v_pk_add_f32 v[50:51], v[50:51], v[52:53]
; DI float bflo(unsigned w) { return __uint_as_float(w << 16); }
; DI float bfhi(unsigned w) { return __uint_as_float(w & 0xffff0000u); }
; DI unsigned cvtpk(float lo, float hi) { unsigned r; asm volatile("v_cvt_pk_bf16_f32 %0, %1, %2" : "=v"(r) : "v"(lo), "v"(hi)); return r; }
; DI float sigmoidf_(float x) { return __builtin_amdgcn_rcpf(1.f + __expf(-x)); }
;     __device__ __forceinline__ void operator()(const f32x4 (&acc)[2][2][4][2], const Unit& u, int wr, int wc, int fr, int fq) const {
;     ...
;             for (int m = 0; m < 4; ++m) {
;                 const int row = u.pm * BM + ai * HALF + wr * 64 + m * 16 + fr;
;                 const int colb = pn * BM + wc * 32 + 8 * fq;
;                 const unsigned goff = (unsigned)(row * LDP + C_GT + br * 1024 + colb), ooff = (unsigned)(row * 1024 + colb);
;                 const bf16_t* gp = proj + goff;
;                 bf16_t* op = out + ooff;
;                 __builtin_amdgcn_sched_barrier(0);
; #pragma unroll
;                 for (int bj = 0; bj < 2; ++bj) {
;                     const u32x4 g = *(const u32x4*)(gp + bj * HALF);
;                     f32x4 v0 = acc[ai][bj][m][0], v1 = acc[ai][bj][m][1];
;                     v0[0] *= sigmoidf_(bflo(g[0])); v0[1] *= sigmoidf_(bfhi(g[0])); v0[2] *= sigmoidf_(bflo(g[1])); v0[3] *= sigmoidf_(bfhi(g[1]));
;                     v1[0] *= sigmoidf_(bflo(g[2])); v1[1] *= sigmoidf_(bfhi(g[2])); v1[2] *= sigmoidf_(bflo(g[3])); v1[3] *= sigmoidf_(bfhi(g[3]));
;                     if (br > 0) {
;                         const u32x4 o = *(const u32x4*)(op + bj * HALF);
;                         v0[0] += bflo(o[0]); v0[1] += bfhi(o[0]); v0[2] += bflo(o[1]); v0[3] += bfhi(o[1]);
;                         v1[0] += bflo(o[2]); v1[1] += bfhi(o[2]); v1[2] += bflo(o[3]); v1[3] += bfhi(o[3]);
;                     }
;                     u32x4 w = {cvtpk(v0[0], v0[1]), cvtpk(v0[2], v0[3]), cvtpk(v1[0], v1[1]), cvtpk(v1[2], v1[3])};
;                     *(u32x4*)(op + bj * HALF) = w;
;                 }
.LBB0_163:
	v_readlane_b32 s80, v255, 8
	v_cvt_pk_bf16_f32 v52, v54, v55
	v_cvt_pk_bf16_f32 v53, v56, v57
	v_cvt_pk_bf16_f32 v54, v58, v59
	v_cvt_pk_bf16_f32 v55, v50, v51
	v_add_u32_e32 v0, v167, v158
	v_or_b32_e32 v50, v166, v159
	v_readlane_b32 s92, v255, 20
	v_readlane_b32 s93, v255, 21
	v_readlane_b32 s94, v255, 22
	v_readlane_b32 s95, v255, 23
	v_mov_b32_e32 v51, v1
	global_store_dwordx4 v[66:67], v[52:55], off offset:256
	v_lshl_add_u64 v[50:51], v[50:51], 1, s[92:93]
	v_readlane_b32 s81, v255, 9
	v_lshl_add_u64 v[52:53], v[0:1], 1, s[94:95]
	v_readlane_b32 s82, v255, 10
	v_readlane_b32 s83, v255, 11
	v_readlane_b32 s84, v255, 12
	v_readlane_b32 s85, v255, 13
	v_readlane_b32 s86, v255, 14
	v_readlane_b32 s87, v255, 15
	v_readlane_b32 s88, v255, 16
	v_readlane_b32 s89, v255, 17
	v_readlane_b32 s90, v255, 18
	v_readlane_b32 s91, v255, 19
	v_add_u32_e32 v178, v167, v160
	v_mov_b32_e32 v179, v1
	v_lshl_add_u64 v[178:179], v[178:179], 1, s[94:95]
	v_or_b32_e32 v180, v166, v161
	v_mov_b32_e32 v181, v1
	v_lshl_add_u64 v[180:181], v[180:181], 1, s[92:93]
	global_load_dwordx4 v[218:221], v[178:179], off
	global_load_dwordx4 v[222:225], v[178:179], off offset:256
	global_load_dwordx4 v[226:229], v[180:181], off
	global_load_dwordx4 v[230:233], v[180:181], off offset:256
	s_and_b64 vcc, exec, s[36:37]
	s_waitcnt vmcnt(7)
	v_mov_b32_e32 v54, v234
	v_mov_b32_e32 v55, v235
	v_mov_b32_e32 v56, v236
	v_mov_b32_e32 v57, v237
	v_lshlrev_b32_e32 v0, 16, v54
	v_mul_f32_e32 v0, 0xbfb8aa3b, v0
	v_exp_f32_e32 v0, v0
	s_nop 0
	v_add_f32_e32 v0, 1.0, v0
	v_rcp_f32_e32 v58, v0
	v_and_b32_e32 v0, 0xffff0000, v54
	v_mul_f32_e32 v0, 0xbfb8aa3b, v0
	v_exp_f32_e32 v0, v0
	s_nop 0
	v_add_f32_e32 v0, 1.0, v0
	v_rcp_f32_e32 v59, v0
	v_lshlrev_b32_e32 v0, 16, v55
	v_mul_f32_e32 v0, 0xbfb8aa3b, v0
	v_exp_f32_e32 v0, v0
	v_pk_mul_f32 v[46:47], v[46:47], v[58:59]
	v_add_f32_e32 v0, 1.0, v0
	v_rcp_f32_e32 v54, v0
	v_and_b32_e32 v0, 0xffff0000, v55
	v_mul_f32_e32 v0, 0xbfb8aa3b, v0
	v_exp_f32_e32 v0, v0
	s_nop 0
	v_add_f32_e32 v0, 1.0, v0
	v_rcp_f32_e32 v55, v0
	v_lshlrev_b32_e32 v0, 16, v56
	v_mul_f32_e32 v0, 0xbfb8aa3b, v0
	v_exp_f32_e32 v0, v0
	v_pk_mul_f32 v[48:49], v[48:49], v[54:55]
	v_add_f32_e32 v0, 1.0, v0
	v_rcp_f32_e32 v54, v0
	v_and_b32_e32 v0, 0xffff0000, v56
	v_mul_f32_e32 v0, 0xbfb8aa3b, v0
	v_exp_f32_e32 v0, v0
	s_nop 0
	v_add_f32_e32 v0, 1.0, v0
	v_rcp_f32_e32 v55, v0
	v_lshlrev_b32_e32 v0, 16, v57
	v_mul_f32_e32 v0, 0xbfb8aa3b, v0
	v_exp_f32_e32 v0, v0
	v_pk_mul_f32 v[42:43], v[42:43], v[54:55]
	v_add_f32_e32 v0, 1.0, v0
	v_rcp_f32_e32 v54, v0
	v_and_b32_e32 v0, 0xffff0000, v57
	v_mul_f32_e32 v0, 0xbfb8aa3b, v0
	v_exp_f32_e32 v0, v0
	s_nop 0
	v_add_f32_e32 v0, 1.0, v0
	v_rcp_f32_e32 v55, v0
	s_nop 0
	v_pk_mul_f32 v[44:45], v[44:45], v[54:55]
	s_cbranch_vccnz .LBB0_165
	s_waitcnt vmcnt(5)
	v_mov_b32_e32 v54, v242
	v_mov_b32_e32 v55, v243
	v_mov_b32_e32 v56, v244
	v_mov_b32_e32 v57, v245
	v_lshlrev_b32_e32 v58, 16, v54
	v_and_b32_e32 v59, 0xffff0000, v54
	v_lshlrev_b32_e32 v54, 16, v55
	v_and_b32_e32 v55, 0xffff0000, v55
	v_pk_add_f32 v[48:49], v[48:49], v[54:55]
	v_lshlrev_b32_e32 v54, 16, v56
	v_and_b32_e32 v55, 0xffff0000, v56
	v_pk_add_f32 v[42:43], v[42:43], v[54:55]
	v_lshlrev_b32_e32 v54, 16, v57
	v_and_b32_e32 v55, 0xffff0000, v57
	v_pk_add_f32 v[46:47], v[46:47], v[58:59]
	v_pk_add_f32 v[44:45], v[44:45], v[54:55]
.LBB0_165:
	v_cvt_pk_bf16_f32 v46, v46, v47
	v_cvt_pk_bf16_f32 v47, v48, v49
	v_cvt_pk_bf16_f32 v48, v42, v43
	s_nop 0
	v_cvt_pk_bf16_f32 v49, v44, v45
	global_store_dwordx4 v[50:51], v[46:49], off
	s_and_b64 vcc, exec, s[36:37]
	s_waitcnt vmcnt(6)
	v_mov_b32_e32 v42, v238
	v_mov_b32_e32 v43, v239
	v_mov_b32_e32 v44, v240
	v_mov_b32_e32 v45, v241
	v_lshlrev_b32_e32 v0, 16, v42
	v_and_b32_e32 v42, 0xffff0000, v42
	v_lshlrev_b32_e32 v46, 16, v43
	v_and_b32_e32 v43, 0xffff0000, v43
	v_lshlrev_b32_e32 v47, 16, v44
	v_and_b32_e32 v44, 0xffff0000, v44
	v_lshlrev_b32_e32 v48, 16, v45
	v_and_b32_e32 v45, 0xffff0000, v45
	v_mul_f32_e32 v0, 0xbfb8aa3b, v0
	v_mul_f32_e32 v42, 0xbfb8aa3b, v42
	v_mul_f32_e32 v46, 0xbfb8aa3b, v46
	v_mul_f32_e32 v43, 0xbfb8aa3b, v43
	v_mul_f32_e32 v47, 0xbfb8aa3b, v47
	v_mul_f32_e32 v44, 0xbfb8aa3b, v44
	v_mul_f32_e32 v48, 0xbfb8aa3b, v48
	v_mul_f32_e32 v45, 0xbfb8aa3b, v45
	v_exp_f32_e32 v0, v0
	v_exp_f32_e32 v42, v42
	v_exp_f32_e32 v46, v46
	v_exp_f32_e32 v43, v43
	v_exp_f32_e32 v47, v47
	v_exp_f32_e32 v44, v44
	v_exp_f32_e32 v48, v48
	v_exp_f32_e32 v45, v45
	v_add_f32_e32 v0, 1.0, v0
	v_add_f32_e32 v49, 1.0, v42
	v_add_f32_e32 v46, 1.0, v46
	v_add_f32_e32 v52, 1.0, v43
	v_add_f32_e32 v47, 1.0, v47
	v_add_f32_e32 v53, 1.0, v44
	v_add_f32_e32 v48, 1.0, v48
	v_add_f32_e32 v54, 1.0, v45
	v_rcp_f32_e32 v42, v0
	v_rcp_f32_e32 v43, v49
	v_rcp_f32_e32 v44, v46
	v_rcp_f32_e32 v45, v52
	v_rcp_f32_e32 v46, v47
	v_rcp_f32_e32 v47, v53
	v_rcp_f32_e32 v48, v48
	v_rcp_f32_e32 v49, v54
	v_pk_mul_f32 v[38:39], v[38:39], v[42:43]
	v_pk_mul_f32 v[40:41], v[40:41], v[44:45]
	v_pk_mul_f32 v[42:43], v[34:35], v[46:47]
	v_pk_mul_f32 v[34:35], v[36:37], v[48:49]
	s_cbranch_vccnz .LBB0_167
	s_waitcnt vmcnt(4)
	v_mov_b32_e32 v44, v174
	v_mov_b32_e32 v45, v175
	v_mov_b32_e32 v46, v176
	v_mov_b32_e32 v47, v177
	v_lshlrev_b32_e32 v36, 16, v44
	v_and_b32_e32 v37, 0xffff0000, v44
	v_pk_add_f32 v[38:39], v[38:39], v[36:37]
	v_lshlrev_b32_e32 v36, 16, v45
	v_and_b32_e32 v37, 0xffff0000, v45
	v_pk_add_f32 v[40:41], v[40:41], v[36:37]
	v_lshlrev_b32_e32 v36, 16, v46
	v_and_b32_e32 v37, 0xffff0000, v46
	v_pk_add_f32 v[42:43], v[42:43], v[36:37]
	v_lshlrev_b32_e32 v36, 16, v47
	v_and_b32_e32 v37, 0xffff0000, v47
	v_pk_add_f32 v[34:35], v[34:35], v[36:37]
; DI float bflo(unsigned w) { return __uint_as_float(w << 16); }
; DI float bfhi(unsigned w) { return __uint_as_float(w & 0xffff0000u); }
; DI unsigned cvtpk(float lo, float hi) { unsigned r; asm volatile("v_cvt_pk_bf16_f32 %0, %1, %2" : "=v"(r) : "v"(lo), "v"(hi)); return r; }
; DI float sigmoidf_(float x) { return __builtin_amdgcn_rcpf(1.f + __expf(-x)); }
;     __device__ __forceinline__ void operator()(const f32x4 (&acc)[2][2][4][2], const Unit& u, int wr, int wc, int fr, int fq) const {
;     ...
;             for (int m = 0; m < 4; ++m) {
;                 const int row = u.pm * BM + ai * HALF + wr * 64 + m * 16 + fr;
;                 const int colb = pn * BM + wc * 32 + 8 * fq;
;                 const unsigned goff = (unsigned)(row * LDP + C_GT + br * 1024 + colb), ooff = (unsigned)(row * 1024 + colb);
;                 const bf16_t* gp = proj + goff;
;                 bf16_t* op = out + ooff;
;                 __builtin_amdgcn_sched_barrier(0);
; #pragma unroll
;                 for (int bj = 0; bj < 2; ++bj) {
;                     const u32x4 g = *(const u32x4*)(gp + bj * HALF);
;                     f32x4 v0 = acc[ai][bj][m][0], v1 = acc[ai][bj][m][1];
;                     v0[0] *= sigmoidf_(bflo(g[0])); v0[1] *= sigmoidf_(bfhi(g[0])); v0[2] *= sigmoidf_(bflo(g[1])); v0[3] *= sigmoidf_(bfhi(g[1]));
;                     v1[0] *= sigmoidf_(bflo(g[2])); v1[1] *= sigmoidf_(bfhi(g[2])); v1[2] *= sigmoidf_(bflo(g[3])); v1[3] *= sigmoidf_(bfhi(g[3]));
;                     if (br > 0) {
;                         const u32x4 o = *(const u32x4*)(op + bj * HALF);
;                         v0[0] += bflo(o[0]); v0[1] += bfhi(o[0]); v0[2] += bflo(o[1]); v0[3] += bfhi(o[1]);
;                         v1[0] += bflo(o[2]); v1[1] += bfhi(o[2]); v1[2] += bflo(o[3]); v1[3] += bfhi(o[3]);
;                     }
;                     u32x4 w = {cvtpk(v0[0], v0[1]), cvtpk(v0[2], v0[3]), cvtpk(v1[0], v1[1]), cvtpk(v1[2], v1[3])};
;                     *(u32x4*)(op + bj * HALF) = w;
;                 }
.LBB0_167:
	v_readlane_b32 s80, v255, 8
	v_cvt_pk_bf16_f32 v36, v38, v39
	v_cvt_pk_bf16_f32 v37, v40, v41
	v_cvt_pk_bf16_f32 v38, v42, v43
	v_cvt_pk_bf16_f32 v39, v34, v35
	v_add_u32_e32 v0, v167, v160
	v_or_b32_e32 v34, v166, v161
	v_readlane_b32 s92, v255, 20
	v_readlane_b32 s93, v255, 21
	v_readlane_b32 s94, v255, 22
	v_readlane_b32 s95, v255, 23
	v_mov_b32_e32 v35, v1
	global_store_dwordx4 v[50:51], v[36:39], off offset:256
	v_lshl_add_u64 v[34:35], v[34:35], 1, s[92:93]
	v_readlane_b32 s81, v255, 9
	v_lshl_add_u64 v[36:37], v[0:1], 1, s[94:95]
	v_readlane_b32 s82, v255, 10
	v_readlane_b32 s83, v255, 11
	v_readlane_b32 s84, v255, 12
	v_readlane_b32 s85, v255, 13
	v_readlane_b32 s86, v255, 14
	v_readlane_b32 s87, v255, 15
	v_readlane_b32 s88, v255, 16
	v_readlane_b32 s89, v255, 17
	v_readlane_b32 s90, v255, 18
	v_readlane_b32 s91, v255, 19
	v_add_u32_e32 v178, v167, v162
	v_mov_b32_e32 v179, v1
	v_lshl_add_u64 v[178:179], v[178:179], 1, s[94:95]
	v_or_b32_e32 v180, v166, v163
	v_mov_b32_e32 v181, v1
	v_lshl_add_u64 v[180:181], v[180:181], 1, s[92:93]
	global_load_dwordx4 v[234:237], v[178:179], off
	global_load_dwordx4 v[238:241], v[178:179], off offset:256
	global_load_dwordx4 v[242:245], v[180:181], off
	global_load_dwordx4 v[174:177], v[180:181], off offset:256
	s_and_b64 vcc, exec, s[36:37]
	s_waitcnt vmcnt(7)
	v_mov_b32_e32 v38, v218
	v_mov_b32_e32 v39, v219
	v_mov_b32_e32 v40, v220
	v_mov_b32_e32 v41, v221
	v_lshlrev_b32_e32 v0, 16, v38
	v_mul_f32_e32 v0, 0xbfb8aa3b, v0
	v_exp_f32_e32 v0, v0
	s_nop 0
	v_add_f32_e32 v0, 1.0, v0
	v_rcp_f32_e32 v42, v0
	v_and_b32_e32 v0, 0xffff0000, v38
	v_mul_f32_e32 v0, 0xbfb8aa3b, v0
	v_exp_f32_e32 v0, v0
	s_nop 0
	v_add_f32_e32 v0, 1.0, v0
	v_rcp_f32_e32 v43, v0
	v_lshlrev_b32_e32 v0, 16, v39
	v_mul_f32_e32 v0, 0xbfb8aa3b, v0
	v_exp_f32_e32 v0, v0
	v_pk_mul_f32 v[30:31], v[30:31], v[42:43]
	v_add_f32_e32 v0, 1.0, v0
	v_rcp_f32_e32 v38, v0
	v_and_b32_e32 v0, 0xffff0000, v39
	v_mul_f32_e32 v0, 0xbfb8aa3b, v0
	v_exp_f32_e32 v0, v0
	s_nop 0
	v_add_f32_e32 v0, 1.0, v0
	v_rcp_f32_e32 v39, v0
	v_lshlrev_b32_e32 v0, 16, v40
	v_mul_f32_e32 v0, 0xbfb8aa3b, v0
	v_exp_f32_e32 v0, v0
	v_pk_mul_f32 v[32:33], v[32:33], v[38:39]
	v_add_f32_e32 v0, 1.0, v0
	v_rcp_f32_e32 v38, v0
	v_and_b32_e32 v0, 0xffff0000, v40
	v_mul_f32_e32 v0, 0xbfb8aa3b, v0
	v_exp_f32_e32 v0, v0
	s_nop 0
	v_add_f32_e32 v0, 1.0, v0
	v_rcp_f32_e32 v39, v0
	v_lshlrev_b32_e32 v0, 16, v41
	v_mul_f32_e32 v0, 0xbfb8aa3b, v0
	v_exp_f32_e32 v0, v0
	v_pk_mul_f32 v[26:27], v[26:27], v[38:39]
	v_add_f32_e32 v0, 1.0, v0
	v_rcp_f32_e32 v38, v0
	v_and_b32_e32 v0, 0xffff0000, v41
	v_mul_f32_e32 v0, 0xbfb8aa3b, v0
	v_exp_f32_e32 v0, v0
	s_nop 0
	v_add_f32_e32 v0, 1.0, v0
	v_rcp_f32_e32 v39, v0
	s_nop 0
	v_pk_mul_f32 v[28:29], v[28:29], v[38:39]
	s_cbranch_vccnz .LBB0_169
	s_waitcnt vmcnt(5)
	v_mov_b32_e32 v38, v226
	v_mov_b32_e32 v39, v227
	v_mov_b32_e32 v40, v228
	v_mov_b32_e32 v41, v229
	v_lshlrev_b32_e32 v42, 16, v38
	v_and_b32_e32 v43, 0xffff0000, v38
	v_lshlrev_b32_e32 v38, 16, v39
	v_and_b32_e32 v39, 0xffff0000, v39
	v_pk_add_f32 v[32:33], v[32:33], v[38:39]
	v_lshlrev_b32_e32 v38, 16, v40
	v_and_b32_e32 v39, 0xffff0000, v40
	v_pk_add_f32 v[26:27], v[26:27], v[38:39]
	v_lshlrev_b32_e32 v38, 16, v41
	v_and_b32_e32 v39, 0xffff0000, v41
	v_pk_add_f32 v[30:31], v[30:31], v[42:43]
	v_pk_add_f32 v[28:29], v[28:29], v[38:39]
.LBB0_169:
	v_cvt_pk_bf16_f32 v30, v30, v31
	v_cvt_pk_bf16_f32 v31, v32, v33
	v_cvt_pk_bf16_f32 v32, v26, v27
	s_nop 0
	v_cvt_pk_bf16_f32 v33, v28, v29
	global_store_dwordx4 v[34:35], v[30:33], off
	s_and_b64 vcc, exec, s[36:37]
	s_waitcnt vmcnt(6)
	v_mov_b32_e32 v26, v222
	v_mov_b32_e32 v27, v223
	v_mov_b32_e32 v28, v224
	v_mov_b32_e32 v29, v225
	v_lshlrev_b32_e32 v0, 16, v26
	v_and_b32_e32 v26, 0xffff0000, v26
	v_lshlrev_b32_e32 v30, 16, v27
	v_and_b32_e32 v27, 0xffff0000, v27
	v_lshlrev_b32_e32 v31, 16, v28
	v_and_b32_e32 v28, 0xffff0000, v28
	v_lshlrev_b32_e32 v32, 16, v29
	v_and_b32_e32 v29, 0xffff0000, v29
	v_mul_f32_e32 v0, 0xbfb8aa3b, v0
	v_mul_f32_e32 v26, 0xbfb8aa3b, v26
	v_mul_f32_e32 v30, 0xbfb8aa3b, v30
	v_mul_f32_e32 v27, 0xbfb8aa3b, v27
	v_mul_f32_e32 v31, 0xbfb8aa3b, v31
	v_mul_f32_e32 v28, 0xbfb8aa3b, v28
	v_mul_f32_e32 v32, 0xbfb8aa3b, v32
	v_mul_f32_e32 v29, 0xbfb8aa3b, v29
	v_exp_f32_e32 v0, v0
	v_exp_f32_e32 v26, v26
	v_exp_f32_e32 v30, v30
	v_exp_f32_e32 v27, v27
	v_exp_f32_e32 v31, v31
	v_exp_f32_e32 v28, v28
	v_exp_f32_e32 v32, v32
	v_exp_f32_e32 v29, v29
	v_add_f32_e32 v0, 1.0, v0
	v_add_f32_e32 v33, 1.0, v26
	v_add_f32_e32 v30, 1.0, v30
	v_add_f32_e32 v36, 1.0, v27
	v_add_f32_e32 v31, 1.0, v31
	v_add_f32_e32 v37, 1.0, v28
	v_add_f32_e32 v32, 1.0, v32
	v_add_f32_e32 v38, 1.0, v29
	v_rcp_f32_e32 v26, v0
	v_rcp_f32_e32 v27, v33
	v_rcp_f32_e32 v28, v30
	v_rcp_f32_e32 v29, v36
	v_rcp_f32_e32 v30, v31
	v_rcp_f32_e32 v31, v37
	v_rcp_f32_e32 v32, v32
	v_rcp_f32_e32 v33, v38
	v_pk_mul_f32 v[22:23], v[22:23], v[26:27]
	v_pk_mul_f32 v[24:25], v[24:25], v[28:29]
	v_pk_mul_f32 v[26:27], v[18:19], v[30:31]
	v_pk_mul_f32 v[18:19], v[20:21], v[32:33]
	s_cbranch_vccnz .LBB0_171
	s_waitcnt vmcnt(4)
	v_mov_b32_e32 v28, v230
	v_mov_b32_e32 v29, v231
	v_mov_b32_e32 v30, v232
	v_mov_b32_e32 v31, v233
	v_lshlrev_b32_e32 v20, 16, v28
	v_and_b32_e32 v21, 0xffff0000, v28
	v_pk_add_f32 v[22:23], v[22:23], v[20:21]
	v_lshlrev_b32_e32 v20, 16, v29
	v_and_b32_e32 v21, 0xffff0000, v29
	v_pk_add_f32 v[24:25], v[24:25], v[20:21]
	v_lshlrev_b32_e32 v20, 16, v30
	v_and_b32_e32 v21, 0xffff0000, v30
	v_pk_add_f32 v[26:27], v[26:27], v[20:21]
	v_lshlrev_b32_e32 v20, 16, v31
	v_and_b32_e32 v21, 0xffff0000, v31
	v_pk_add_f32 v[18:19], v[18:19], v[20:21]
; DI float bflo(unsigned w) { return __uint_as_float(w << 16); }
; DI float bfhi(unsigned w) { return __uint_as_float(w & 0xffff0000u); }
; DI unsigned cvtpk(float lo, float hi) { unsigned r; asm volatile("v_cvt_pk_bf16_f32 %0, %1, %2" : "=v"(r) : "v"(lo), "v"(hi)); return r; }
; DI float sigmoidf_(float x) { return __builtin_amdgcn_rcpf(1.f + __expf(-x)); }
;     __device__ __forceinline__ void operator()(const f32x4 (&acc)[2][2][4][2], const Unit& u, int wr, int wc, int fr, int fq) const {
;     ...
;             for (int m = 0; m < 4; ++m) {
;                 const int row = u.pm * BM + ai * HALF + wr * 64 + m * 16 + fr;
;                 const int colb = pn * BM + wc * 32 + 8 * fq;
;                 const unsigned goff = (unsigned)(row * LDP + C_GT + br * 1024 + colb), ooff = (unsigned)(row * 1024 + colb);
;                 const bf16_t* gp = proj + goff;
;                 bf16_t* op = out + ooff;
;                 __builtin_amdgcn_sched_barrier(0);
; #pragma unroll
;                 for (int bj = 0; bj < 2; ++bj) {
;                     const u32x4 g = *(const u32x4*)(gp + bj * HALF);
;                     f32x4 v0 = acc[ai][bj][m][0], v1 = acc[ai][bj][m][1];
;                     v0[0] *= sigmoidf_(bflo(g[0])); v0[1] *= sigmoidf_(bfhi(g[0])); v0[2] *= sigmoidf_(bflo(g[1])); v0[3] *= sigmoidf_(bfhi(g[1]));
;                     v1[0] *= sigmoidf_(bflo(g[2])); v1[1] *= sigmoidf_(bfhi(g[2])); v1[2] *= sigmoidf_(bflo(g[3])); v1[3] *= sigmoidf_(bfhi(g[3]));
;                     if (br > 0) {
;                         const u32x4 o = *(const u32x4*)(op + bj * HALF);
;                         v0[0] += bflo(o[0]); v0[1] += bfhi(o[0]); v0[2] += bflo(o[1]); v0[3] += bfhi(o[1]);
;                         v1[0] += bflo(o[2]); v1[1] += bfhi(o[2]); v1[2] += bflo(o[3]); v1[3] += bfhi(o[3]);
;                     }
;                     u32x4 w = {cvtpk(v0[0], v0[1]), cvtpk(v0[2], v0[3]), cvtpk(v1[0], v1[1]), cvtpk(v1[2], v1[3])};
;                     *(u32x4*)(op + bj * HALF) = w;
;                 }
.LBB0_171:
	v_readlane_b32 s80, v255, 8
	v_cvt_pk_bf16_f32 v20, v22, v23
	v_cvt_pk_bf16_f32 v21, v24, v25
	v_cvt_pk_bf16_f32 v22, v26, v27
	v_cvt_pk_bf16_f32 v23, v18, v19
	v_add_u32_e32 v0, v167, v162
	v_or_b32_e32 v18, v166, v163
	v_readlane_b32 s92, v255, 20
	v_readlane_b32 s93, v255, 21
	v_readlane_b32 s94, v255, 22
	v_readlane_b32 s95, v255, 23
	v_mov_b32_e32 v19, v1
	global_store_dwordx4 v[34:35], v[20:23], off offset:256
	v_lshl_add_u64 v[18:19], v[18:19], 1, s[92:93]
	v_readlane_b32 s81, v255, 9
	v_lshl_add_u64 v[20:21], v[0:1], 1, s[94:95]
	v_readlane_b32 s82, v255, 10
	v_readlane_b32 s83, v255, 11
	v_readlane_b32 s84, v255, 12
	v_readlane_b32 s85, v255, 13
	v_readlane_b32 s86, v255, 14
	v_readlane_b32 s87, v255, 15
	v_readlane_b32 s88, v255, 16
	v_readlane_b32 s89, v255, 17
	v_readlane_b32 s90, v255, 18
	v_readlane_b32 s91, v255, 19
	s_and_b64 vcc, exec, s[36:37]
	s_waitcnt vmcnt(3)
	v_mov_b32_e32 v22, v234
	v_mov_b32_e32 v23, v235
	v_mov_b32_e32 v24, v236
	v_mov_b32_e32 v25, v237
	v_lshlrev_b32_e32 v0, 16, v22
	v_mul_f32_e32 v0, 0xbfb8aa3b, v0
	v_exp_f32_e32 v0, v0
	s_nop 0
	v_add_f32_e32 v0, 1.0, v0
	v_rcp_f32_e32 v26, v0
	v_and_b32_e32 v0, 0xffff0000, v22
	v_mul_f32_e32 v0, 0xbfb8aa3b, v0
	v_exp_f32_e32 v0, v0
	s_nop 0
	v_add_f32_e32 v0, 1.0, v0
	v_rcp_f32_e32 v27, v0
	v_lshlrev_b32_e32 v0, 16, v23
	v_mul_f32_e32 v0, 0xbfb8aa3b, v0
	v_exp_f32_e32 v0, v0
	v_pk_mul_f32 v[14:15], v[14:15], v[26:27]
	v_add_f32_e32 v0, 1.0, v0
	v_rcp_f32_e32 v22, v0
	v_and_b32_e32 v0, 0xffff0000, v23
	v_mul_f32_e32 v0, 0xbfb8aa3b, v0
	v_exp_f32_e32 v0, v0
	s_nop 0
	v_add_f32_e32 v0, 1.0, v0
	v_rcp_f32_e32 v23, v0
	v_lshlrev_b32_e32 v0, 16, v24
	v_mul_f32_e32 v0, 0xbfb8aa3b, v0
	v_exp_f32_e32 v0, v0
	v_pk_mul_f32 v[16:17], v[16:17], v[22:23]
	v_add_f32_e32 v0, 1.0, v0
	v_rcp_f32_e32 v22, v0
	v_and_b32_e32 v0, 0xffff0000, v24
	v_mul_f32_e32 v0, 0xbfb8aa3b, v0
	v_exp_f32_e32 v0, v0
	s_nop 0
	v_add_f32_e32 v0, 1.0, v0
	v_rcp_f32_e32 v23, v0
	v_lshlrev_b32_e32 v0, 16, v25
	v_mul_f32_e32 v0, 0xbfb8aa3b, v0
	v_exp_f32_e32 v0, v0
	v_pk_mul_f32 v[10:11], v[10:11], v[22:23]
	v_add_f32_e32 v0, 1.0, v0
	v_rcp_f32_e32 v22, v0
	v_and_b32_e32 v0, 0xffff0000, v25
	v_mul_f32_e32 v0, 0xbfb8aa3b, v0
	v_exp_f32_e32 v0, v0
	s_nop 0
	v_add_f32_e32 v0, 1.0, v0
	v_rcp_f32_e32 v23, v0
	s_nop 0
	v_pk_mul_f32 v[12:13], v[12:13], v[22:23]
	s_cbranch_vccnz .LBB0_173
	s_waitcnt vmcnt(1)
	v_mov_b32_e32 v22, v242
	v_mov_b32_e32 v23, v243
	v_mov_b32_e32 v24, v244
	v_mov_b32_e32 v25, v245
	v_lshlrev_b32_e32 v26, 16, v22
	v_and_b32_e32 v27, 0xffff0000, v22
	v_lshlrev_b32_e32 v22, 16, v23
	v_and_b32_e32 v23, 0xffff0000, v23
	v_pk_add_f32 v[16:17], v[16:17], v[22:23]
	v_lshlrev_b32_e32 v22, 16, v24
	v_and_b32_e32 v23, 0xffff0000, v24
	v_pk_add_f32 v[10:11], v[10:11], v[22:23]
	v_lshlrev_b32_e32 v22, 16, v25
	v_and_b32_e32 v23, 0xffff0000, v25
	v_pk_add_f32 v[14:15], v[14:15], v[26:27]
	v_pk_add_f32 v[12:13], v[12:13], v[22:23]
.LBB0_173:
	v_cvt_pk_bf16_f32 v14, v14, v15
	v_cvt_pk_bf16_f32 v15, v16, v17
	v_cvt_pk_bf16_f32 v16, v10, v11
	s_nop 0
	v_cvt_pk_bf16_f32 v17, v12, v13
	global_store_dwordx4 v[18:19], v[14:17], off
	s_and_b64 vcc, exec, s[36:37]
	s_waitcnt vmcnt(2)
	v_mov_b32_e32 v10, v238
	v_mov_b32_e32 v11, v239
	v_mov_b32_e32 v12, v240
	v_mov_b32_e32 v13, v241
	v_lshlrev_b32_e32 v0, 16, v10
	v_and_b32_e32 v10, 0xffff0000, v10
	v_lshlrev_b32_e32 v14, 16, v11
	v_and_b32_e32 v11, 0xffff0000, v11
	v_lshlrev_b32_e32 v15, 16, v12
	v_and_b32_e32 v12, 0xffff0000, v12
	v_lshlrev_b32_e32 v16, 16, v13
	v_and_b32_e32 v13, 0xffff0000, v13
	v_mul_f32_e32 v0, 0xbfb8aa3b, v0
	v_mul_f32_e32 v10, 0xbfb8aa3b, v10
	v_mul_f32_e32 v14, 0xbfb8aa3b, v14
	v_mul_f32_e32 v11, 0xbfb8aa3b, v11
	v_mul_f32_e32 v15, 0xbfb8aa3b, v15
	v_mul_f32_e32 v12, 0xbfb8aa3b, v12
	v_mul_f32_e32 v16, 0xbfb8aa3b, v16
	v_mul_f32_e32 v13, 0xbfb8aa3b, v13
	v_exp_f32_e32 v0, v0
	v_exp_f32_e32 v10, v10
	v_exp_f32_e32 v14, v14
	v_exp_f32_e32 v11, v11
	v_exp_f32_e32 v15, v15
	v_exp_f32_e32 v12, v12
	v_exp_f32_e32 v16, v16
	v_exp_f32_e32 v13, v13
	v_add_f32_e32 v0, 1.0, v0
	v_add_f32_e32 v17, 1.0, v10
	v_add_f32_e32 v14, 1.0, v14
	v_add_f32_e32 v20, 1.0, v11
	v_add_f32_e32 v15, 1.0, v15
	v_add_f32_e32 v21, 1.0, v12
	v_add_f32_e32 v16, 1.0, v16
	v_add_f32_e32 v22, 1.0, v13
	v_rcp_f32_e32 v10, v0
	v_rcp_f32_e32 v11, v17
	v_rcp_f32_e32 v12, v14
	v_rcp_f32_e32 v13, v20
	v_rcp_f32_e32 v14, v15
	v_rcp_f32_e32 v15, v21
	v_rcp_f32_e32 v16, v16
	v_rcp_f32_e32 v17, v22
	v_pk_mul_f32 v[6:7], v[6:7], v[10:11]
	v_pk_mul_f32 v[8:9], v[8:9], v[12:13]
	v_pk_mul_f32 v[10:11], v[2:3], v[14:15]
	v_pk_mul_f32 v[2:3], v[4:5], v[16:17]
	s_cbranch_vccnz .LBB0_175
	s_waitcnt vmcnt(0)
	v_mov_b32_e32 v12, v174
	v_mov_b32_e32 v13, v175
	v_mov_b32_e32 v14, v176
	v_mov_b32_e32 v15, v177
	v_lshlrev_b32_e32 v4, 16, v12
	v_and_b32_e32 v5, 0xffff0000, v12
	v_pk_add_f32 v[6:7], v[6:7], v[4:5]
	v_lshlrev_b32_e32 v4, 16, v13
	v_and_b32_e32 v5, 0xffff0000, v13
	v_pk_add_f32 v[8:9], v[8:9], v[4:5]
	v_lshlrev_b32_e32 v4, 16, v14
	v_and_b32_e32 v5, 0xffff0000, v14
	v_pk_add_f32 v[10:11], v[10:11], v[4:5]
	v_lshlrev_b32_e32 v4, 16, v15
	v_and_b32_e32 v5, 0xffff0000, v15
	v_pk_add_f32 v[2:3], v[2:3], v[4:5]
